# FFN-down GEMMs process their three tile rounds in reverse (most recently written activation rows first) so the A operand is still in the Infinity Cache
# baseline (speedup 1.0000x reference)
;     __host__ __device__ bool next(int i, Unit& u) const {
;         const long L = (long)i * G + c; if (L >= nwg) return false;
;         int wgid = (int)L; { const int q = nwg / NXCD, r = nwg % NXCD, xcd = wgid % NXCD, off = wgid / NXCD; wgid = (xcd < r ? xcd * (q + 1) : r * (q + 1) + (xcd - r) * q) + off; }
;         const int nig = WGM * nN, gid = wgid / nig, fm = gid * WGM, gsz = (nM - fm) < WGM ? (nM - fm) : WGM;
;         u.pm = fm + ((wgid % nig) % gsz); u.pn = (wgid % nig) / gsz; return true;
;     }
; __global__ void __launch_bounds__(NWAVES * 64, 2) mega_fwd(Args args) {
;     ...
;     if (IN(2)) {
;         pg8::Gemm g{ACT, W1out, M, DM, DFF}; pg8::StaticOrder S; S.init(M, DM, G, bx);
.LBB0_251:
	s_or_b64 exec, exec, s[0:1]
	s_cmp_lt_i32 s30, 3
	s_cselect_b64 s[0:1], -1, 0
	s_cmp_gt_i32 s31, 2
	s_cselect_b64 s[2:3], -1, 0
	s_and_b64 s[0:1], s[0:1], s[2:3]
	s_andn2_b64 vcc, exec, s[0:1]
	s_waitcnt lgkmcnt(0)
	s_barrier
	s_cbranch_vccnz .LBB0_286
	s_cmpk_lt_i32 s10, 0x300
	s_cselect_b64 s[0:1], -1, 0
	s_cmpk_gt_i32 s10, 0x2ff
	v_readfirstlane_b32 s26, v230
	s_cbranch_scc1 .LBB0_254
	s_cmp_eq_u32 s11, 0x100
	s_cselect_b32 s98, 0x200, 0
	s_add_i32 s10, s10, s98
	s_ashr_i32 s2, s10, 31
	s_lshr_b32 s2, s2, 29
	s_add_i32 s2, s10, s2
	s_ashr_i32 s3, s2, 3
	s_and_b32 s2, s2, -8
	s_sub_i32 s2, s10, s2
	s_cmp_lt_i32 s2, 0
	s_movk_i32 s4, 0x61
	s_cselect_b32 s4, s4, 0x60
	s_mul_i32 s2, s2, s4
	s_add_i32 s2, s2, s3
	s_ashr_i32 s3, s2, 31
	s_lshr_b32 s3, s3, 27
	s_add_i32 s3, s2, s3
	s_ashr_i32 s4, s3, 5
	s_andn2_b32 s3, s3, 31
	s_sub_i32 s2, s2, s3
	s_bfe_i32 s3, s2, 0x80000
	s_bfe_u32 s3, s3, 0x3000c
	s_add_i32 s3, s2, s3
	s_bfe_i32 s5, s3, 0x80000
	s_and_b32 s3, s3, 0xf8
	s_sub_i32 s2, s2, s3
	s_lshl_b32 s4, s4, 3
	s_sext_i32_i16 s5, s5
	s_sext_i32_i8 s2, s2
	s_add_i32 s83, s4, s2
	s_ashr_i32 s82, s5, 3
	s_sub_i32 s10, s10, s98

;     __host__ __device__ bool next(int i, Unit& u) const {
;         const long L = (long)i * G + c; if (L >= nwg) return false;
;         int wgid = (int)L; { const int q = nwg / NXCD, r = nwg % NXCD, xcd = wgid % NXCD, off = wgid / NXCD; wgid = (xcd < r ? xcd * (q + 1) : r * (q + 1) + (xcd - r) * q) + off; }
;         const int nig = WGM * nN, gid = wgid / nig, fm = gid * WGM, gsz = (nM - fm) < WGM ? (nM - fm) : WGM;
;         u.pm = fm + ((wgid % nig) % gsz); u.pn = (wgid % nig) / gsz; return true;
;     }
; template <class Epi, class Sched, bool ALIGN_EPI = false, bool SP2 = false>
; __device__ __forceinline__ void gemm_phase(PG8_LAS unsigned char* lds, const Gemm g, const Sched& S, const Epi& E) {
;     ...
;         const bool has_next = S.next(ui + 1, nxt);
.LBB0_259:
	s_add_i32 s44, s44, 1
	s_mul_i32 s0, s44, s47
	s_mul_hi_u32 s1, s44, s11
	s_add_i32 s1, s1, s0
	s_mul_i32 s0, s44, s11
	s_add_u32 s6, s0, s10
	s_addc_u32 s7, s1, s48
	v_cmp_gt_i64_e64 s[4:5], s[6:7], v[158:159]
	v_cmp_lt_i64_e64 s[0:1], s[6:7], v[156:157]
	s_and_b64 vcc, exec, s[4:5]
	s_cbranch_vccnz .LBB0_261
	s_cmp_eq_u32 s98, 0
	s_cbranch_scc1 .Lrev_p2_skip
	s_lshl_b32 s99, s10, 1
	s_add_i32 s99, s99, s98
	s_sub_i32 s6, s99, s6
.Lrev_p2_skip:
	s_ashr_i32 s7, s6, 31
	s_lshr_b32 s7, s7, 29
	s_add_i32 s7, s6, s7
	s_ashr_i32 s24, s7, 3
	s_and_b32 s7, s7, -8
	s_sub_i32 s6, s6, s7
	s_cmp_lt_i32 s6, 0
	s_cselect_b32 s7, s61, 0x60
	s_mul_i32 s6, s6, s7
	s_add_i32 s6, s6, s24
	s_ashr_i32 s7, s6, 31
	s_lshr_b32 s7, s7, 27
	s_add_i32 s7, s6, s7
	s_ashr_i32 s24, s7, 5
	s_lshl_b32 s24, s24, 3
	s_sub_i32 s25, 0xc0, s24
	s_min_i32 s25, s25, 8
	s_abs_i32 s80, s25
	v_cvt_f32_u32_e32 v0, s80
	s_sub_i32 s84, 0, s80
	s_andn2_b32 s7, s7, 31
	s_sub_i32 s6, s6, s7
	v_rcp_iflag_f32_e32 v0, v0
	s_abs_i32 s7, s6
	s_xor_b32 s81, s6, s25
	s_ashr_i32 s81, s81, 31
	v_mul_f32_e32 v0, 0x4f7ffffe, v0
	v_cvt_u32_f32_e32 v0, v0
	s_nop 0
	v_readfirstlane_b32 s85, v0
	s_mul_i32 s84, s84, s85
	s_mul_hi_u32 s84, s85, s84
	s_add_i32 s85, s85, s84
	s_mul_hi_u32 s84, s7, s85
	s_mul_i32 s85, s84, s80
	s_sub_i32 s7, s7, s85
	s_add_i32 s86, s84, 1
	s_sub_i32 s85, s7, s80
	s_cmp_ge_u32 s7, s80
	s_cselect_b32 s84, s86, s84
	s_cselect_b32 s7, s85, s7
	s_add_i32 s85, s84, 1
	s_cmp_ge_u32 s7, s80
	s_cselect_b32 s7, s85, s84
	s_xor_b32 s7, s7, s81
	s_sub_i32 s80, s7, s81
	s_mul_i32 s7, s80, s25
	s_sub_i32 s6, s6, s7
	s_add_i32 s81, s24, s6

;     __host__ __device__ bool next(int i, Unit& u) const {
;         const long L = (long)i * G + c; if (L >= nwg) return false;
;         int wgid = (int)L; { const int q = nwg / NXCD, r = nwg % NXCD, xcd = wgid % NXCD, off = wgid / NXCD; wgid = (xcd < r ? xcd * (q + 1) : r * (q + 1) + (xcd - r) * q) + off; }
;         const int nig = WGM * nN, gid = wgid / nig, fm = gid * WGM, gsz = (nM - fm) < WGM ? (nM - fm) : WGM;
;         u.pm = fm + ((wgid % nig) % gsz); u.pn = (wgid % nig) / gsz; return true;
;     }
; __global__ void __launch_bounds__(NWAVES * 64, 2) mega_fwd(Args args) {
;     ...
;     if (IN(10)) {
;         pg8::Gemm g{ACT, W2out, M, DM, DFF}; pg8::StaticOrder S; S.init(M, DM, G, bx);
.LBB0_954:
	s_or_b64 exec, exec, s[0:1]
	s_cmp_lt_i32 s30, 11
	s_cselect_b64 s[0:1], -1, 0
	s_cmp_gt_i32 s31, 10
	s_cselect_b64 s[2:3], -1, 0
	s_and_b64 s[0:1], s[0:1], s[2:3]
	s_andn2_b64 vcc, exec, s[0:1]
	s_waitcnt lgkmcnt(0)
	s_barrier
	s_cbranch_vccnz .LBB0_1010
	s_cmpk_lt_i32 s10, 0x300
	s_cselect_b64 s[0:1], -1, 0
	s_cmpk_gt_i32 s10, 0x2ff
	v_readfirstlane_b32 s2, v230
	s_cbranch_scc1 .LBB0_957
	s_cmp_eq_u32 s11, 0x100
	s_cselect_b32 s98, 0x200, 0
	s_add_i32 s10, s10, s98
	s_ashr_i32 s3, s10, 31
	s_lshr_b32 s3, s3, 29
	s_add_i32 s3, s10, s3
	s_ashr_i32 s4, s3, 3
	s_and_b32 s3, s3, -8
	s_sub_i32 s3, s10, s3
	s_cmp_lt_i32 s3, 0
	s_movk_i32 s5, 0x61
	s_cselect_b32 s5, s5, 0x60
	s_mul_i32 s3, s3, s5
	s_add_i32 s3, s3, s4
	s_ashr_i32 s4, s3, 31
	s_lshr_b32 s4, s4, 27
	s_add_i32 s4, s3, s4
	s_ashr_i32 s5, s4, 5
	s_and_b32 s4, s4, 0xffe0
	s_sub_i32 s3, s3, s4
	s_bfe_i32 s4, s3, 0x80000
	s_bfe_u32 s4, s4, 0x3000c
	s_add_i32 s4, s3, s4
	s_bfe_i32 s6, s4, 0x80000
	s_and_b32 s4, s4, 0xf8
	s_sub_i32 s3, s3, s4
	s_lshl_b32 s5, s5, 3
	s_sext_i32_i16 s6, s6
	s_sext_i32_i8 s3, s3
	s_add_i32 s71, s5, s3
	s_ashr_i32 s42, s6, 3
	s_sub_i32 s10, s10, s98

;     __host__ __device__ bool next(int i, Unit& u) const {
;         const long L = (long)i * G + c; if (L >= nwg) return false;
;         int wgid = (int)L; { const int q = nwg / NXCD, r = nwg % NXCD, xcd = wgid % NXCD, off = wgid / NXCD; wgid = (xcd < r ? xcd * (q + 1) : r * (q + 1) + (xcd - r) * q) + off; }
;         const int nig = WGM * nN, gid = wgid / nig, fm = gid * WGM, gsz = (nM - fm) < WGM ? (nM - fm) : WGM;
;         u.pm = fm + ((wgid % nig) % gsz); u.pn = (wgid % nig) / gsz; return true;
;     }
; template <class Epi, class Sched, bool ALIGN_EPI = false, bool SP2 = false>
; __device__ __forceinline__ void gemm_phase(PG8_LAS unsigned char* lds, const Gemm g, const Sched& S, const Epi& E) {
;     ...
;         const bool has_next = S.next(ui + 1, nxt);
.LBB0_963:
	s_add_i32 s52, s52, 1
	s_mul_i32 s2, s52, s63
	s_mul_hi_u32 s3, s52, s11
	s_add_i32 s3, s3, s2
	s_mul_i32 s2, s52, s11
	s_add_u32 s2, s2, s10
	s_addc_u32 s3, s3, s64
	v_cmp_gt_i64_e32 vcc, s[2:3], v[142:143]
	v_cmp_lt_i64_e64 s[4:5], s[2:3], v[140:141]
	s_cbranch_vccnz .LBB0_965
	s_cmp_eq_u32 s98, 0
	s_cbranch_scc1 .Lrev_p10_skip
	s_lshl_b32 s99, s10, 1
	s_add_i32 s99, s99, s98
	s_sub_i32 s2, s99, s2
.Lrev_p10_skip:
	s_ashr_i32 s3, s2, 31
	s_lshr_b32 s3, s3, 29
	s_add_i32 s3, s2, s3
	s_ashr_i32 s38, s3, 3
	s_and_b32 s3, s3, -8
	s_sub_i32 s2, s2, s3
	s_cmp_lt_i32 s2, 0
	s_cselect_b32 s3, s65, 0x60
	s_mul_i32 s2, s2, s3
	s_add_i32 s2, s2, s38
	s_ashr_i32 s3, s2, 31
	s_lshr_b32 s3, s3, 27
	s_add_i32 s3, s2, s3
	s_ashr_i32 s38, s3, 5
	s_lshl_b32 s38, s38, 3
	s_sub_i32 s39, 0xc0, s38
	s_min_i32 s39, s39, 8
	s_abs_i32 s40, s39
	v_cvt_f32_u32_e32 v0, s40
	s_sub_i32 s43, 0, s40
	s_andn2_b32 s3, s3, 31
	s_sub_i32 s2, s2, s3
	v_rcp_iflag_f32_e32 v0, v0
	s_abs_i32 s3, s2
	s_xor_b32 s41, s2, s39
	s_ashr_i32 s41, s41, 31
	v_mul_f32_e32 v0, 0x4f7ffffe, v0
	v_cvt_u32_f32_e32 v0, v0
	s_nop 0
	v_readfirstlane_b32 s69, v0
	s_mul_i32 s43, s43, s69
	s_mul_hi_u32 s43, s69, s43
	s_add_i32 s69, s69, s43
	s_mul_hi_u32 s43, s3, s69
	s_mul_i32 s69, s43, s40
	s_sub_i32 s3, s3, s69
	s_add_i32 s70, s43, 1
	s_sub_i32 s69, s3, s40
	s_cmp_ge_u32 s3, s40
	s_cselect_b32 s43, s70, s43
	s_cselect_b32 s3, s69, s3
	s_add_i32 s69, s43, 1
	s_cmp_ge_u32 s3, s40
	s_cselect_b32 s3, s69, s43
	s_xor_b32 s3, s3, s41
	s_sub_i32 s69, s3, s41
	s_mul_i32 s3, s69, s39
	s_sub_i32 s2, s2, s3
	s_add_i32 s70, s38, s2
